# MLA K-fragment reads: one address register with immediate offsets for both tiles (one fewer VALU and SALU per iteration)
# speedup vs baseline: 1.0008x; 1.0008x over previous
; template <int DQ>
; DI void attn_dense_item(const u16* __restrict__ Q, int qh, const u16* __restrict__ Kp, int HK, int kh, const u16* __restrict__ Vt,
;                         int S, int s0, int qblk, u16* __restrict__ MER, int ocol, float* __restrict__ ssqo, int slot, unsigned char* smem) {
;     ...
;   for (int kt = 0; kt < nkt; kt += 2) {
;     const int sb = (kt & 2), nb = sb ^ 2;
;     TILE_X2(sb, kt == 0); TILE_Y2(sb);
.LBB0_300:
	s_add_i32 s6, s14, -4
	s_and_b32 s6, s6, 2
	s_mul_i32 s7, s6, 0x3400
	v_add3_u32 v225, v198, s7, v199
	s_mul_i32 s7, s6, 0x2400
	ds_read_b128 v[226:229], v225
	ds_read_b128 v[230:233], v225 offset:32
	ds_read_b128 v[234:237], v225 offset:64
	ds_read_b128 v[238:241], v225 offset:96
	ds_read_b128 v[242:245], v225 offset:128
	ds_read_b128 v[162:165], v225 offset:160
	ds_read_b128 v[166:169], v225 offset:6656

.Lmla_B_st_end:
	v_add_f32_e32 v201, v74, v201
	v_add_f32_e32 v247, v75, v76
	v_add_f32_e32 v201, v77, v201
	v_add_f32_e32 v247, v78, v247
	s_waitcnt lgkmcnt(6)
	v_mfma_f32_32x32x16_bf16 v[50:65], v[226:229], v[114:117], v[34:49]
	ds_read_b128 v[226:229], v225 offset:6688
	v_add_f32_e32 v201, v79, v201
	v_add_f32_e32 v247, v80, v247
	v_add_f32_e32 v201, v81, v201
	v_add_f32_e32 v247, v82, v247
	v_add_f32_e32 v201, v83, v201
	v_add_f32_e32 v247, v84, v247
	s_waitcnt lgkmcnt(6)
	v_mfma_f32_32x32x16_bf16 v[50:65], v[230:233], v[118:121], v[50:65]
	ds_read_b128 v[230:233], v225 offset:6720
	v_add_f32_e32 v201, v85, v201
	v_add_f32_e32 v247, v86, v247
	v_add_f32_e32 v201, v87, v201
	v_add_f32_e32 v247, v88, v247
	v_add_f32_e32 v201, v89, v201
	v_add_f32_e32 v247, v90, v247
	s_waitcnt lgkmcnt(6)
	v_mfma_f32_32x32x16_bf16 v[50:65], v[234:237], v[122:125], v[50:65]
	ds_read_b128 v[234:237], v225 offset:6752

.Lmla_B_ls_end:
	s_add_i32 s6, s14, -4
	s_and_b32 s6, s6, 2
	s_mul_i32 s7, s6, 0x2400
	v_add_f32_e32 v201, v91, v201
	v_add_f32_e32 v247, v92, v247
	v_add_f32_e32 v201, v93, v201
	v_add_f32_e32 v247, v94, v247
	v_add_f32_e32 v201, v95, v201
	v_add_f32_e32 v247, v96, v247
	s_waitcnt lgkmcnt(6)
	v_mfma_f32_32x32x16_bf16 v[50:65], v[238:241], v[126:129], v[50:65]
	ds_read_b128 v[238:241], v225 offset:6784
	v_add_f32_e32 v201, v97, v201
	v_add_f32_e32 v247, v98, v247
	v_add_f32_e32 v201, v99, v201
	v_add_f32_e32 v247, v100, v247
	v_add_f32_e32 v201, v101, v201
	v_add_f32_e32 v247, v102, v247
	s_waitcnt lgkmcnt(6)
	v_mfma_f32_32x32x16_bf16 v[50:65], v[242:245], v[130:133], v[50:65]
	ds_read_b128 v[242:245], v225 offset:6816
	v_add_f32_e32 v201, v103, v201
	v_add_f32_e32 v247, v104, v247
	v_add_f32_e32 v201, v105, v201
	v_add_f32_e32 v247, v106, v247
	v_add_f32_e32 v201, v107, v201
	v_add_f32_e32 v247, v108, v247
	s_waitcnt lgkmcnt(6)
	v_mfma_f32_32x32x16_bf16 v[50:65], v[162:165], v[134:137], v[50:65]
	ds_read_b128 v[162:165], v225 offset:13312
	v_add_f32_e32 v201, v109, v201
	v_add_f32_e32 v247, v110, v247
	v_add_f32_e32 v201, v111, v201
	v_add_f32_e32 v247, v112, v247
	v_add_f32_e32 v201, v113, v201
	v_add_f32_e32 v247, v246, v247
	s_waitcnt lgkmcnt(6)
	v_mfma_f32_32x32x16_bf16 v[66:81], v[166:169], v[114:117], v[34:49]
	ds_read_b128 v[166:169], v225 offset:13344
	v_add_f32_e32 v201, v202, v201
	v_add_f32_e32 v247, v203, v247
	v_add_f32_e32 v201, v204, v201
	v_add_f32_e32 v247, v205, v247
	s_waitcnt lgkmcnt(6)
	v_mfma_f32_32x32x16_bf16 v[66:81], v[226:229], v[118:121], v[66:81]
	ds_read_b128 v[226:229], v225 offset:13376
	v_add_f32_e32 v201, v206, v201
	v_add_f32_e32 v247, v207, v247
	v_add_f32_e32 v201, v208, v201
	v_add_f32_e32 v247, v209, v247
	s_waitcnt lgkmcnt(6)
	v_mfma_f32_32x32x16_bf16 v[66:81], v[230:233], v[122:125], v[66:81]
	ds_read_b128 v[230:233], v225 offset:13408
	v_add_f32_e32 v201, v210, v201
	v_add_f32_e32 v247, v211, v247
	v_add_f32_e32 v201, v212, v201
	v_add_f32_e32 v247, v213, v247
	v_max3_f32 v0, v50, v51, v52
	v_max3_f32 v0, v0, v53, v54
	s_waitcnt lgkmcnt(6)
	v_mfma_f32_32x32x16_bf16 v[66:81], v[234:237], v[126:129], v[66:81]
	ds_read_b128 v[234:237], v225 offset:13440
	v_add_f32_e32 v201, v214, v201
	v_add_f32_e32 v247, v215, v247
	v_add_f32_e32 v201, v216, v201
	v_add_f32_e32 v247, v217, v247
	v_max3_f32 v0, v0, v55, v56
	v_max3_f32 v0, v0, v57, v58
	s_waitcnt lgkmcnt(6)
	v_mfma_f32_32x32x16_bf16 v[66:81], v[238:241], v[130:133], v[66:81]
	ds_read_b128 v[238:241], v225 offset:13472
	v_add_f32_e32 v201, v218, v201
	v_add_f32_e32 v247, v219, v247
	v_add_f32_e32 v201, v220, v201
	v_add_f32_e32 v247, v221, v247
	v_max3_f32 v0, v0, v59, v60
	v_max3_f32 v0, v0, v61, v62
	s_waitcnt lgkmcnt(6)
	v_mfma_f32_32x32x16_bf16 v[66:81], v[242:245], v[134:137], v[66:81]
	ds_read_b128 v[242:245], v225 offset:19968
	v_add_f32_e32 v201, v222, v201
	v_add_f32_e32 v247, v223, v247
	v_add_f32_e32 v201, v224, v201
	v_add_f32_e32 v201, v247, v201
	v_max3_f32 v0, v0, v63, v64
	v_max3_f32 v0, v0, v65, v65
	s_waitcnt lgkmcnt(6)
	v_mfma_f32_32x32x16_bf16 v[82:97], v[162:165], v[114:117], v[34:49]
	ds_read_b128 v[162:165], v225 offset:20000
	v_exp_f32_e32 v246, v50
	v_exp_f32_e32 v202, v51
	s_waitcnt lgkmcnt(6)
	v_mfma_f32_32x32x16_bf16 v[82:97], v[166:169], v[118:121], v[82:97]
	ds_read_b128 v[166:169], v225 offset:20032
	v_add3_u32 v247, v198, s7, v200
	v_exp_f32_e32 v203, v52
	v_exp_f32_e32 v204, v53
	s_waitcnt lgkmcnt(6)
	v_mfma_f32_32x32x16_bf16 v[82:97], v[226:229], v[122:125], v[82:97]
	ds_read_b128 v[226:229], v225 offset:20064
	v_max3_f32 v0, v0, v66, v67
	v_max3_f32 v0, v0, v68, v69
	v_exp_f32_e32 v205, v54
	v_exp_f32_e32 v206, v55
	s_waitcnt lgkmcnt(6)
	v_mfma_f32_32x32x16_bf16 v[82:97], v[230:233], v[126:129], v[82:97]
	ds_read_b128 v[230:233], v225 offset:20096
	v_max3_f32 v0, v0, v70, v71
	v_max3_f32 v0, v0, v72, v73
	v_exp_f32_e32 v207, v56
	v_exp_f32_e32 v208, v57
	s_waitcnt lgkmcnt(6)
	v_mfma_f32_32x32x16_bf16 v[82:97], v[234:237], v[130:133], v[82:97]
	ds_read_b128 v[234:237], v225 offset:20128
	v_max3_f32 v0, v0, v74, v75
	v_max3_f32 v0, v0, v76, v77
	v_exp_f32_e32 v211, v60
	v_exp_f32_e32 v212, v61
	s_waitcnt lgkmcnt(6)
	v_mfma_f32_32x32x16_bf16 v[82:97], v[238:241], v[134:137], v[82:97]
	ds_read_b128 v[238:241], v247 offset:53248
	v_max3_f32 v0, v0, v78, v79
	v_max3_f32 v0, v0, v80, v81
	v_exp_f32_e32 v213, v62
	v_exp_f32_e32 v214, v63
	s_waitcnt lgkmcnt(6)
	v_mfma_f32_32x32x16_bf16 v[98:113], v[242:245], v[114:117], v[34:49]
	ds_read_b128 v[242:245], v247 offset:57856
	v_exp_f32_e32 v215, v64
	v_exp_f32_e32 v216, v65
	s_waitcnt lgkmcnt(6)
	v_mfma_f32_32x32x16_bf16 v[98:113], v[162:165], v[118:121], v[98:113]
	s_waitcnt lgkmcnt(5)
	v_mfma_f32_32x32x16_bf16 v[98:113], v[166:169], v[122:125], v[98:113]
	s_waitcnt lgkmcnt(4)
	v_mfma_f32_32x32x16_bf16 v[98:113], v[226:229], v[126:129], v[98:113]
	ds_read_b128 v[226:229], v247 offset:53280
	s_waitcnt lgkmcnt(4)
	v_mfma_f32_32x32x16_bf16 v[98:113], v[230:233], v[130:133], v[98:113]
	ds_read_b128 v[230:233], v247 offset:57888
	s_waitcnt lgkmcnt(4)
	v_mfma_f32_32x32x16_bf16 v[98:113], v[234:237], v[134:137], v[98:113]
	ds_read_b128 v[234:237], v247 offset:53312
	v_max3_f32 v0, v0, v82, v83
	v_max3_f32 v0, v0, v84, v85
	v_max3_f32 v0, v0, v86, v87
	v_max3_f32 v0, v0, v88, v89
	v_max3_f32 v0, v0, v90, v91
	v_max3_f32 v0, v0, v92, v93
	v_max3_f32 v0, v0, v94, v95
	v_max3_f32 v0, v0, v96, v97
	s_nop 4
	v_max3_f32 v0, v0, v98, v99
	v_max3_f32 v0, v0, v100, v101
	v_max3_f32 v0, v0, v102, v103
	v_max3_f32 v0, v0, v104, v105
	v_max3_f32 v0, v0, v106, v107
	v_max3_f32 v0, v0, v108, v109
	v_max3_f32 v0, v0, v110, v111
	v_max3_f32 v0, v0, v112, v113
	v_mov_b32_e32 v162, v0
	s_nop 1
	v_permlane32_swap_b32_e32 v0, v162
	v_max_f32_e32 v0, v0, v162
	v_cmp_lt_f32_e32 vcc, s50, v0
	s_cbranch_vccz .LBB0_302
	v_max_f32_e32 v0, v0, v0
	v_max_f32_e32 v0, 0, v0
	v_exp_f32_e64 v162, -v0
	v_pk_add_f32 v[50:51], v[50:51], v[0:1] op_sel_hi:[1,0] neg_lo:[0,1] neg_hi:[0,1]
	v_pk_add_f32 v[66:67], v[66:67], v[0:1] op_sel_hi:[1,0] neg_lo:[0,1] neg_hi:[0,1]
	v_pk_add_f32 v[82:83], v[82:83], v[0:1] op_sel_hi:[1,0] neg_lo:[0,1] neg_hi:[0,1]
	v_mul_f32_e32 v201, v201, v162
	v_pk_mul_f32 v[16:17], v[16:17], v[162:163] op_sel_hi:[1,0]
	v_pk_mul_f32 v[14:15], v[14:15], v[162:163] op_sel_hi:[1,0]
	v_pk_mul_f32 v[12:13], v[12:13], v[162:163] op_sel_hi:[1,0]
	v_pk_mul_f32 v[10:11], v[10:11], v[162:163] op_sel_hi:[1,0]
	v_pk_mul_f32 v[8:9], v[8:9], v[162:163] op_sel_hi:[1,0]
	v_pk_mul_f32 v[6:7], v[6:7], v[162:163] op_sel_hi:[1,0]
	v_pk_mul_f32 v[4:5], v[4:5], v[162:163] op_sel_hi:[1,0]
	v_pk_mul_f32 v[2:3], v[2:3], v[162:163] op_sel_hi:[1,0]
	v_pk_mul_f32 v[32:33], v[32:33], v[162:163] op_sel_hi:[1,0]
	v_pk_mul_f32 v[30:31], v[30:31], v[162:163] op_sel_hi:[1,0]
	v_pk_mul_f32 v[28:29], v[28:29], v[162:163] op_sel_hi:[1,0]
	v_pk_mul_f32 v[26:27], v[26:27], v[162:163] op_sel_hi:[1,0]
	v_pk_mul_f32 v[24:25], v[24:25], v[162:163] op_sel_hi:[1,0]
	v_pk_mul_f32 v[22:23], v[22:23], v[162:163] op_sel_hi:[1,0]
	v_pk_mul_f32 v[20:21], v[20:21], v[162:163] op_sel_hi:[1,0]
	v_pk_mul_f32 v[18:19], v[18:19], v[162:163] op_sel_hi:[1,0]
	v_pk_add_f32 v[98:99], v[98:99], v[0:1] op_sel_hi:[1,0] neg_lo:[0,1] neg_hi:[0,1]
	v_pk_add_f32 v[52:53], v[52:53], v[0:1] op_sel_hi:[1,0] neg_lo:[0,1] neg_hi:[0,1]
	v_pk_add_f32 v[68:69], v[68:69], v[0:1] op_sel_hi:[1,0] neg_lo:[0,1] neg_hi:[0,1]
	v_pk_add_f32 v[84:85], v[84:85], v[0:1] op_sel_hi:[1,0] neg_lo:[0,1] neg_hi:[0,1]
	v_pk_add_f32 v[100:101], v[100:101], v[0:1] op_sel_hi:[1,0] neg_lo:[0,1] neg_hi:[0,1]
	v_pk_add_f32 v[54:55], v[54:55], v[0:1] op_sel_hi:[1,0] neg_lo:[0,1] neg_hi:[0,1]
	v_pk_add_f32 v[70:71], v[70:71], v[0:1] op_sel_hi:[1,0] neg_lo:[0,1] neg_hi:[0,1]
	v_pk_add_f32 v[86:87], v[86:87], v[0:1] op_sel_hi:[1,0] neg_lo:[0,1] neg_hi:[0,1]
	v_pk_add_f32 v[102:103], v[102:103], v[0:1] op_sel_hi:[1,0] neg_lo:[0,1] neg_hi:[0,1]
	v_pk_add_f32 v[56:57], v[56:57], v[0:1] op_sel_hi:[1,0] neg_lo:[0,1] neg_hi:[0,1]
	v_pk_add_f32 v[72:73], v[72:73], v[0:1] op_sel_hi:[1,0] neg_lo:[0,1] neg_hi:[0,1]
	v_pk_add_f32 v[88:89], v[88:89], v[0:1] op_sel_hi:[1,0] neg_lo:[0,1] neg_hi:[0,1]
	v_pk_add_f32 v[104:105], v[104:105], v[0:1] op_sel_hi:[1,0] neg_lo:[0,1] neg_hi:[0,1]
	v_pk_add_f32 v[58:59], v[58:59], v[0:1] op_sel_hi:[1,0] neg_lo:[0,1] neg_hi:[0,1]
	v_pk_add_f32 v[74:75], v[74:75], v[0:1] op_sel_hi:[1,0] neg_lo:[0,1] neg_hi:[0,1]
	v_pk_add_f32 v[90:91], v[90:91], v[0:1] op_sel_hi:[1,0] neg_lo:[0,1] neg_hi:[0,1]
	v_pk_add_f32 v[106:107], v[106:107], v[0:1] op_sel_hi:[1,0] neg_lo:[0,1] neg_hi:[0,1]
	v_pk_add_f32 v[60:61], v[60:61], v[0:1] op_sel_hi:[1,0] neg_lo:[0,1] neg_hi:[0,1]
	v_pk_add_f32 v[76:77], v[76:77], v[0:1] op_sel_hi:[1,0] neg_lo:[0,1] neg_hi:[0,1]
	v_pk_add_f32 v[92:93], v[92:93], v[0:1] op_sel_hi:[1,0] neg_lo:[0,1] neg_hi:[0,1]
	v_pk_add_f32 v[108:109], v[108:109], v[0:1] op_sel_hi:[1,0] neg_lo:[0,1] neg_hi:[0,1]
	v_pk_add_f32 v[62:63], v[62:63], v[0:1] op_sel_hi:[1,0] neg_lo:[0,1] neg_hi:[0,1]
	v_pk_add_f32 v[78:79], v[78:79], v[0:1] op_sel_hi:[1,0] neg_lo:[0,1] neg_hi:[0,1]
	v_pk_add_f32 v[94:95], v[94:95], v[0:1] op_sel_hi:[1,0] neg_lo:[0,1] neg_hi:[0,1]
	v_pk_add_f32 v[110:111], v[110:111], v[0:1] op_sel_hi:[1,0] neg_lo:[0,1] neg_hi:[0,1]
	v_pk_add_f32 v[64:65], v[64:65], v[0:1] op_sel_hi:[1,0] neg_lo:[0,1] neg_hi:[0,1]
	v_pk_add_f32 v[80:81], v[80:81], v[0:1] op_sel_hi:[1,0] neg_lo:[0,1] neg_hi:[0,1]
	v_pk_add_f32 v[96:97], v[96:97], v[0:1] op_sel_hi:[1,0] neg_lo:[0,1] neg_hi:[0,1]
	v_pk_add_f32 v[112:113], v[112:113], v[0:1] op_sel_hi:[1,0] neg_lo:[0,1] neg_hi:[0,1]
	v_sub_f32_e32 v49, v49, v0
	v_sub_f32_e32 v48, v48, v0
	v_sub_f32_e32 v47, v47, v0
	v_sub_f32_e32 v46, v46, v0
	v_sub_f32_e32 v45, v45, v0
	v_sub_f32_e32 v44, v44, v0
	v_sub_f32_e32 v43, v43, v0
	v_sub_f32_e32 v42, v42, v0
	v_sub_f32_e32 v41, v41, v0
	v_sub_f32_e32 v40, v40, v0
	v_sub_f32_e32 v39, v39, v0
	v_sub_f32_e32 v38, v38, v0
	v_sub_f32_e32 v37, v37, v0
	v_sub_f32_e32 v36, v36, v0
	v_sub_f32_e32 v35, v35, v0
	v_sub_f32_e32 v34, v34, v0
	v_mul_f32_e32 v246, v246, v162
	v_mul_f32_e32 v202, v202, v162
	v_mul_f32_e32 v203, v203, v162
	v_mul_f32_e32 v204, v204, v162
	v_mul_f32_e32 v205, v205, v162
	v_mul_f32_e32 v206, v206, v162
	v_mul_f32_e32 v207, v207, v162
	v_mul_f32_e32 v208, v208, v162
	v_mul_f32_e32 v211, v211, v162
	v_mul_f32_e32 v212, v212, v162
	v_mul_f32_e32 v213, v213, v162
	v_mul_f32_e32 v214, v214, v162
	v_mul_f32_e32 v215, v215, v162
	v_mul_f32_e32 v216, v216, v162
